# P0: softmax-shift bound (RS) computed one head per workgroup on the last 24 workgroups instead of 8 serialized heads per wave on one workgroup
# speedup vs baseline: 1.0030x; 1.0030x over previous
; __device__ __forceinline__ void phase0(const Args& a, LAS unsigned char* lds, int tid, int lane, int wave) {
;     ...
;     if (bx == G - 1 && wave < 3) {
;         for (int hd = wave * 8; hd < wave * 8 + 8; ++hd) {
;             float gqm = fabsf(a.qw[hd * 64 + lane]), gkm = fabsf(a.kw[hd * 64 + lane]);
; #pragma unroll
;             for (int o = 1; o < 64; o <<= 1) { gqm = fmaxf(gqm, __shfl_xor(gqm, o)); gkm = fmaxf(gkm, __shfl_xor(gkm, o)); }
;             if (lane == 0) ((float*)(a.ws + WS_RS))[hd] = 8.08f * LOG2E * gqm * gkm;
;         }
.LBB0_56:
	s_lshr_b32 s85, s86, 6
	v_and_b32_e32 v186, 63, v178
	v_mbcnt_lo_u32_b32 v187, -1, 0
	s_mov_b32 s100, 0
	s_cmpk_lt_u32 s54, 24
	s_cbranch_scc1 .Lrs_orig
	s_add_i32 s0, s54, 0xffffffe8
	s_sub_i32 s101, s2, s0
	s_cmp_ge_i32 s101, 0
	s_cselect_b64 s[0:1], -1, 0
	s_cmpk_lt_u32 s86, 0x40
	s_cselect_b64 s[4:5], -1, 0
	s_and_b64 s[0:1], s[4:5], s[0:1]
	s_mov_b32 s100, 1
	s_and_b64 vcc, exec, s[0:1]
	s_cbranch_vccz .LBB0_61
	s_branch .Lrs_go
.Lrs_orig:
	s_add_i32 s0, s54, -1
	s_cmp_eq_u32 s2, s0
	s_cselect_b64 s[0:1], -1, 0
	s_cmpk_lt_u32 s86, 0xc0
	s_cselect_b64 s[4:5], -1, 0
	s_and_b64 s[0:1], s[4:5], s[0:1]
	s_and_b64 vcc, exec, s[0:1]
	s_cbranch_vccz .LBB0_61
.Lrs_go:
	v_mbcnt_hi_u32_b32 v0, -1, v187
	v_and_b32_e32 v1, 64, v0
	v_add_u32_e32 v1, 64, v1
	v_xor_b32_e32 v2, 1, v0
	v_cmp_lt_i32_e64 s[0:1], v2, v1
	v_xor_b32_e32 v3, 2, v0
	v_xor_b32_e32 v4, 4, v0
	v_cndmask_b32_e64 v2, v0, v2, s[0:1]
	v_cmp_lt_i32_e64 s[0:1], v3, v1
	v_xor_b32_e32 v5, 8, v0
	v_xor_b32_e32 v6, 16, v0
	v_cndmask_b32_e64 v3, v0, v3, s[0:1]
	v_cmp_lt_i32_e64 s[0:1], v4, v1
	v_xor_b32_e32 v7, 32, v0
	v_cmp_eq_u32_e32 vcc, 0, v186
	v_cndmask_b32_e64 v4, v0, v4, s[0:1]
	v_cmp_lt_i32_e64 s[0:1], v5, v1
	v_lshlrev_b32_e32 v2, 2, v2
	v_lshlrev_b32_e32 v3, 2, v3
	v_cndmask_b32_e64 v5, v0, v5, s[0:1]
	v_cmp_lt_i32_e64 s[0:1], v6, v1
	v_lshlrev_b32_e32 v4, 2, v4
	v_lshlrev_b32_e32 v5, 2, v5
	v_cndmask_b32_e64 v6, v0, v6, s[0:1]
	v_cmp_lt_i32_e64 s[0:1], v7, v1
	v_lshlrev_b32_e32 v6, 2, v6
	v_mov_b32_e32 v1, 0
	v_cndmask_b32_e64 v0, v0, v7, s[0:1]
	s_lshr_b32 s0, s86, 1
	s_and_b32 s0, s0, 0x7fffffe0
	s_add_u32 s0, s52, s0
	s_addc_u32 s1, s53, 0
	s_add_u32 s6, s0, 0xf00000
	v_lshlrev_b32_e32 v7, 2, v0
	s_addc_u32 s7, s1, 0
	v_lshl_or_b32 v0, s85, 9, v186
	s_mov_b64 s[0:1], 0
	s_cmp_eq_u32 s100, 0
	s_cbranch_scc1 .Lrs_setup_done
	v_lshl_or_b32 v0, s101, 6, v186
	s_lshl_b32 s6, s101, 2
	s_add_u32 s6, s52, s6
	s_addc_u32 s7, s53, 0
	s_add_u32 s6, s6, 0xefffe4
	s_addc_u32 s7, s7, 0
	s_mov_b64 s[0:1], 28
.Lrs_setup_done:
	s_branch .LBB0_59
.LBB0_58:
	s_or_b64 exec, exec, s[4:5]
	s_add_u32 s0, s0, 4
	s_addc_u32 s1, s1, 0
	s_cmp_lg_u32 s0, 32
	v_add_u32_e32 v0, 64, v0
	s_cbranch_scc0 .LBB0_61
